# P7 row-statistic exchange fetches all four granules per poll (two 16-byte loads) instead of three sequential polls; on top of tables moved into the in-proj GEMM idle tail
# speedup vs baseline: 1.0894x; 1.0005x over previous
; #define PG8_LAS __attribute__((address_space(3)))
;     __device__ __forceinline__ void fused(f32x4 (&acc)[2][2][4][2], const Unit& u, int wr, int wc, int fr, int fq, PG8_LAS unsigned char* lds, int wid, int lane) const {
;     ...
;         asm volatile("s_waitcnt lgkmcnt(0)" ::: "memory"); __builtin_amdgcn_s_barrier(); asm volatile("" ::: "memory");
;         const int tid = wid * 64 + lane;
;         if (tid < 256) { const f32x4 p = *(const PG8_LAS f32x4*)(Pp + tid * 4); const float mine = (p[0] + p[1]) + (p[2] + p[3]);
;             unsigned long long* sl = slots + (size_t)(u.pm * BM + tid) * 4;
;             __hip_atomic_store(sl + u.pn, (1ull << 32) | (unsigned long long)__float_as_uint(mine), __ATOMIC_RELAXED, __HIP_MEMORY_SCOPE_AGENT);
;             float tot = 0.f;
; #pragma unroll
;             for (int t = 0; t < 4; ++t) { float val = mine;
;                 if (t != u.pn) { unsigned long long v; unsigned sp = 0;
;                     for (;;) { v = __hip_atomic_load(sl + t, __ATOMIC_RELAXED, __HIP_MEMORY_SCOPE_AGENT); if ((unsigned)(v >> 32) == 1u || ++sp > (1u << 22)) break; __builtin_amdgcn_s_sleep(1); }
;                     val = __uint_as_float((unsigned)v); }
;                 tot += val; }
;             S[tid] = __builtin_amdgcn_rsqf(tot * (1.0f / 1024.0f) + 1e-6f); }
.LBB0_832:
	s_or_b64 exec, exec, s[0:1]
	s_waitcnt lgkmcnt(0)
	s_barrier
	s_andn2_b32 s5, s5, 63
	s_waitcnt lgkmcnt(0)
	v_or_b32_e32 v1, s5, v232
	s_movk_i32 s0, 0x100
	v_cmp_gt_i32_e32 vcc, s0, v1
	s_and_saveexec_b64 s[2:3], vcc
	s_cbranch_execz .LBB0_858
	v_lshl_add_u32 v0, v1, 4, 0
	ds_read_b128 v[2:5], v0
	v_add_u32_e32 v6, s12, v1
	v_ashrrev_i32_e32 v7, 31, v6
	s_mov_b64 s[0:1], 0x1700000
	s_ashr_i32 s5, s4, 31
	s_waitcnt lgkmcnt(0)
	v_mov_b32_e32 v8, v3
	v_mov_b32_e32 v9, v4
	v_mov_b32_e32 v3, v5
	v_lshlrev_b64 v[4:5], 5, v[6:7]
	v_lshl_add_u64 v[4:5], s[54:55], 0, v[4:5]
	v_pk_add_f32 v[2:3], v[8:9], v[2:3]
	v_lshl_add_u64 v[4:5], v[4:5], 0, s[0:1]
	v_add_f32_e32 v2, v2, v3
	v_lshl_add_u64 v[6:7], s[4:5], 3, v[4:5]
	v_mov_b32_e32 v3, 1
	s_mov_b32 s6, 0
	global_store_dwordx2 v[6:7], v[2:3], off sc1
	s_mov_b32 s7, 0x40000
.Lp7_xpoll:
	global_load_dwordx4 v[6:9], v[4:5], off sc1
	global_load_dwordx4 v[10:13], v[4:5], off offset:16 sc1
	s_waitcnt vmcnt(0)
	s_cmp_lg_u32 s4, 0
	s_cbranch_scc1 .Lp7_xown0
	v_mov_b32_e32 v6, v2
	v_mov_b32_e32 v7, 1
.Lp7_xown0:
	s_cmp_lg_u32 s4, 1
	s_cbranch_scc1 .Lp7_xown1
	v_mov_b32_e32 v8, v2
	v_mov_b32_e32 v9, 1
.Lp7_xown1:
	s_cmp_lg_u32 s4, 2
	s_cbranch_scc1 .Lp7_xown2
	v_mov_b32_e32 v10, v2
	v_mov_b32_e32 v11, 1
.Lp7_xown2:
	s_cmp_lg_u32 s4, 3
	s_cbranch_scc1 .Lp7_xown3
	v_mov_b32_e32 v12, v2
	v_mov_b32_e32 v13, 1
.Lp7_xown3:
	v_cmp_ne_u32_e32 vcc, 1, v7
	v_cmp_ne_u32_e64 s[8:9], 1, v9
	v_cmp_ne_u32_e64 s[10:11], 1, v11
	v_cmp_ne_u32_e64 s[14:15], 1, v13
	s_or_b64 s[8:9], vcc, s[8:9]
	s_or_b64 s[10:11], s[10:11], s[14:15]
	s_or_b64 s[8:9], s[8:9], s[10:11]
	s_cmp_eq_u64 s[8:9], 0
	s_cbranch_scc1 .Lp7_xdone
	s_add_i32 s7, s7, -1
	s_cmp_eq_u32 s7, 0
	s_cbranch_scc1 .Lp7_xdone
	s_sleep 1
	s_branch .Lp7_xpoll
.Lp7_xdone:
	v_mov_b32_e32 v2, v12
